# S step: an active wave issues its K fragment reads before staging the next tile (ds_writes and the global loads of tile e+3 hide under the LDS read latency)
# baseline (speedup 1.0000x reference)
.Lsb16_step_0:
	s_and_b32 s38, s25, 63
	v_readlane_b32 s32, v136, s38
	v_readlane_b32 s38, v137, s38
	s_bitcmp1_b32 s25, 6
	s_cselect_b32 s77, s38, s32
	s_and_b32 s56, s77, s86
	s_and_b32 s57, s77, s87
	s_or_b32 s28, s56, s57
	s_cmp_eq_u32 s28, 0
	s_cbranch_scc1 .Lsb16_idle_0
	s_and_b32 s38, s25, 63
	v_readlane_b32 s32, v133, s38
	v_readlane_b32 s38, v148, s38
	s_bitcmp1_b32 s25, 6
	s_cselect_b32 s76, s38, s32
	ds_read_b128 v[50:53], v234
	ds_read_b128 v[54:57], v234 offset:64
	ds_read_b128 v[58:61], v234 offset:2304
	ds_read_b128 v[62:65], v234 offset:2368
	ds_read_b128 v[138:141], v234 offset:4608
	ds_read_b128 v[142:145], v234 offset:4672
	s_add_i32 s58, s25, 1
	s_cmp_ge_u32 s58, s101
	s_cbranch_scc1 .Lsb16_nost_a_0
	s_add_i32 s58, s25, 2
	s_cmp_ge_u32 s58, s101
	s_cbranch_scc1 .Lsb16_w0_a_0
	s_waitcnt vmcnt(4)
	s_branch .Lsb16_wr_a_0

.Lsb16_wr_a_0:
	ds_write_b128 v153, v[240:243] offset:18432
	ds_write_b128 v153, v[244:247] offset:27648
	ds_write_b128 v155, v[248:251] offset:18432
	ds_write_b128 v155, v[252:255] offset:27648
	s_add_i32 s58, s25, 3
	s_cmp_ge_u32 s58, s101
	s_cbranch_scc1 .Lsb16_done_a_0
	s_and_b32 s38, s58, 63
	v_readlane_b32 s32, v133, s38
	v_readlane_b32 s38, v148, s38
	s_bitcmp1_b32 s58, 6
	s_cselect_b32 s32, s38, s32
	s_lshl_b32 s32, s32, 13
	s_add_u32 s28, s20, s32
	s_addc_u32 s29, s21, 0
	s_add_u32 s82, s22, s32
	s_addc_u32 s83, s23, 0
	global_load_dwordx4 v[240:243], v134, s[28:29]
	global_load_dwordx4 v[244:247], v134, s[82:83]
	global_load_dwordx4 v[248:251], v135, s[28:29]
	global_load_dwordx4 v[252:255], v135, s[82:83]
	s_branch .Lsb16_done_a_0

.Lsb16_done_a_0:
	s_cmp_eq_u32 s56, 0
	s_cbranch_scc1 .Lsb16_g1only_0
	v_subrev_u32_e32 v146, s94, v236
	v_lshrrev_b32_e64 v146, v146, s77
	v_and_b32_e32 v146, 1, v146
	v_cmp_ne_u32_e32 vcc, 0, v146
	s_nop 1
	v_cndmask_b32_e32 v146, v213, v100, vcc
	s_waitcnt lgkmcnt(9)
	v_mfma_f32_16x16x32_bf16 v[34:37], v[50:53], v[66:69], 0
	s_waitcnt lgkmcnt(8)
	v_mfma_f32_16x16x32_bf16 v[34:37], v[54:57], v[70:73], v[34:37]
	ds_read_b128 v[50:53], v234 offset:6912
	ds_read_b128 v[54:57], v234 offset:6976
	s_waitcnt lgkmcnt(9)
	v_mfma_f32_16x16x32_bf16 v[38:41], v[58:61], v[66:69], 0
	s_waitcnt lgkmcnt(8)
	v_mfma_f32_16x16x32_bf16 v[38:41], v[62:65], v[70:73], v[38:41]
	ds_read_b128 v[58:61], v234 offset:9216
	ds_read_b128 v[62:65], v234 offset:9280
	s_waitcnt lgkmcnt(9)
	v_mfma_f32_16x16x32_bf16 v[42:45], v[138:141], v[66:69], 0
	s_waitcnt lgkmcnt(8)
	v_mfma_f32_16x16x32_bf16 v[42:45], v[142:145], v[70:73], v[42:45]
	s_waitcnt lgkmcnt(3)
	v_mfma_f32_16x16x32_bf16 v[46:49], v[50:53], v[66:69], 0
	s_waitcnt lgkmcnt(2)
	v_mfma_f32_16x16x32_bf16 v[46:49], v[54:57], v[70:73], v[46:49]
	ds_read_b128 v[50:53], v234 offset:11520
	ds_read_b128 v[54:57], v234 offset:11584
	v_fma_f32 v34, v34, s48, v146
	v_fma_f32 v35, v35, s48, v146
	v_fma_f32 v36, v36, s48, v146
	v_fma_f32 v37, v37, s48, v146
	v_fma_f32 v38, v38, s48, v146
	v_fma_f32 v39, v39, s48, v146
	v_fma_f32 v40, v40, s48, v146
	v_fma_f32 v41, v41, s48, v146
	v_fma_f32 v42, v42, s48, v146
	v_fma_f32 v43, v43, s48, v146
	v_fma_f32 v44, v44, s48, v146
	v_fma_f32 v45, v45, s48, v146
	v_fma_f32 v46, v46, s48, v146
	v_fma_f32 v47, v47, s48, v146
	v_fma_f32 v48, v48, s48, v146
	v_fma_f32 v49, v49, s48, v146
	s_cmp_lg_u32 s76, s72
	s_cbranch_scc1 .Lsb16_nm0_0a
	s_lshl_b32 s83, s76, 6
	v_subrev_u32_e32 v146, s83, v239
	v_cmp_le_i32_e64 s[28:29], 0, v146
	s_nop 1
	v_cndmask_b32_e64 v34, v213, v34, s[28:29]
	v_cmp_le_i32_e64 s[28:29], 1, v146
	s_nop 1
	v_cndmask_b32_e64 v35, v213, v35, s[28:29]
	v_cmp_le_i32_e64 s[28:29], 2, v146
	s_nop 1
	v_cndmask_b32_e64 v36, v213, v36, s[28:29]
	v_cmp_le_i32_e64 s[28:29], 3, v146
	s_nop 1
	v_cndmask_b32_e64 v37, v213, v37, s[28:29]
	v_cmp_le_i32_e64 s[28:29], 16, v146
	s_nop 1
	v_cndmask_b32_e64 v38, v213, v38, s[28:29]
	v_cmp_le_i32_e64 s[28:29], 17, v146
	s_nop 1
	v_cndmask_b32_e64 v39, v213, v39, s[28:29]
	v_cmp_le_i32_e64 s[28:29], 18, v146
	s_nop 1
	v_cndmask_b32_e64 v40, v213, v40, s[28:29]
	v_cmp_le_i32_e64 s[28:29], 19, v146
	s_nop 1
	v_cndmask_b32_e64 v41, v213, v41, s[28:29]
	v_cmp_le_i32_e64 s[28:29], 32, v146
	s_nop 1
	v_cndmask_b32_e64 v42, v213, v42, s[28:29]
	v_cmp_le_i32_e64 s[28:29], 33, v146
	s_nop 1
	v_cndmask_b32_e64 v43, v213, v43, s[28:29]
	v_cmp_le_i32_e64 s[28:29], 34, v146
	s_nop 1
	v_cndmask_b32_e64 v44, v213, v44, s[28:29]
	v_cmp_le_i32_e64 s[28:29], 35, v146
	s_nop 1
	v_cndmask_b32_e64 v45, v213, v45, s[28:29]
	v_cmp_le_i32_e64 s[28:29], 48, v146
	s_nop 1
	v_cndmask_b32_e64 v46, v213, v46, s[28:29]
	v_cmp_le_i32_e64 s[28:29], 49, v146
	s_nop 1
	v_cndmask_b32_e64 v47, v213, v47, s[28:29]
	v_cmp_le_i32_e64 s[28:29], 50, v146
	s_nop 1
	v_cndmask_b32_e64 v48, v213, v48, s[28:29]
	v_cmp_le_i32_e64 s[28:29], 51, v146
	s_nop 1
	v_cndmask_b32_e64 v49, v213, v49, s[28:29]
.Lsb16_nm0_0a:
	v_exp_f32_e32 v34, v34
	v_exp_f32_e32 v35, v35
	v_exp_f32_e32 v36, v36
	v_exp_f32_e32 v37, v37
	v_exp_f32_e32 v38, v38
	v_exp_f32_e32 v39, v39
	v_exp_f32_e32 v40, v40
	v_exp_f32_e32 v41, v41
	v_exp_f32_e32 v42, v42
	v_exp_f32_e32 v43, v43
	v_exp_f32_e32 v44, v44
	v_exp_f32_e32 v45, v45
	v_exp_f32_e32 v46, v46
	v_exp_f32_e32 v47, v47
	v_exp_f32_e32 v48, v48
	v_exp_f32_e32 v49, v49
	v_add_f32_e32 v138, v34, v35
	v_add_f32_e32 v139, v36, v37
	v_add_f32_e32 v140, v38, v39
	v_add_f32_e32 v141, v40, v41
	v_add_f32_e32 v138, v138, v42
	v_add_f32_e32 v139, v139, v43
	v_add_f32_e32 v140, v140, v44
	v_add_f32_e32 v141, v141, v45
	v_add_f32_e32 v138, v138, v46
	v_add_f32_e32 v139, v139, v47
	v_add_f32_e32 v140, v140, v48
	v_add_f32_e32 v141, v141, v49
	v_add_f32_e32 v138, v138, v139
	v_add_f32_e32 v140, v140, v141
	v_add_f32_e32 v138, v138, v140
	v_add_f32_e32 v129, v129, v138
	v_cvt_pk_bf16_f32 v138, v34, v35
	v_cvt_pk_bf16_f32 v139, v36, v37
	v_cvt_pk_bf16_f32 v140, v38, v39
	v_cvt_pk_bf16_f32 v141, v40, v41
	v_cvt_pk_bf16_f32 v142, v42, v43
	v_cvt_pk_bf16_f32 v143, v44, v45
	v_cvt_pk_bf16_f32 v144, v46, v47
	v_cvt_pk_bf16_f32 v145, v48, v49
	ds_read_b128 v[34:37], v234 offset:13824
	ds_read_b128 v[38:41], v234 offset:13888
	ds_read_b128 v[42:45], v234 offset:16128
	ds_read_b128 v[46:49], v234 offset:16192
	s_waitcnt lgkmcnt(7)
	v_mfma_f32_16x16x32_bf16 v[2:5], v[58:61], v[138:141], v[2:5]
	s_waitcnt lgkmcnt(6)
	v_mfma_f32_16x16x32_bf16 v[2:5], v[62:65], v[142:145], v[2:5]
	s_waitcnt lgkmcnt(5)
	v_mfma_f32_16x16x32_bf16 v[6:9], v[50:53], v[138:141], v[6:9]
	s_waitcnt lgkmcnt(4)
	v_mfma_f32_16x16x32_bf16 v[6:9], v[54:57], v[142:145], v[6:9]
	s_waitcnt lgkmcnt(3)
	v_mfma_f32_16x16x32_bf16 v[10:13], v[34:37], v[138:141], v[10:13]
	s_waitcnt lgkmcnt(2)
	v_mfma_f32_16x16x32_bf16 v[10:13], v[38:41], v[142:145], v[10:13]
	s_waitcnt lgkmcnt(1)
	v_mfma_f32_16x16x32_bf16 v[14:17], v[42:45], v[138:141], v[14:17]
	s_waitcnt lgkmcnt(0)
	v_mfma_f32_16x16x32_bf16 v[14:17], v[46:49], v[142:145], v[14:17]
	s_cmp_eq_u32 s57, 0
	s_cbranch_scc1 .Lsb16_end_0
	ds_read_b128 v[50:53], v234
	ds_read_b128 v[54:57], v234 offset:64
	ds_read_b128 v[58:61], v234 offset:2304
	ds_read_b128 v[62:65], v234 offset:2368
	ds_read_b128 v[138:141], v234 offset:4608
	ds_read_b128 v[142:145], v234 offset:4672
	v_subrev_u32_e32 v146, s94, v236
	v_add_u32_e32 v146, 2, v146
	v_lshrrev_b32_e64 v146, v146, s77
	v_and_b32_e32 v146, 1, v146
	v_cmp_ne_u32_e32 vcc, 0, v146
	s_nop 1
	v_cndmask_b32_e32 v146, v213, v100, vcc
	s_waitcnt lgkmcnt(5)
	v_mfma_f32_16x16x32_bf16 v[34:37], v[50:53], v[74:77], 0
	s_waitcnt lgkmcnt(4)
	v_mfma_f32_16x16x32_bf16 v[34:37], v[54:57], v[78:81], v[34:37]
	ds_read_b128 v[50:53], v234 offset:6912
	ds_read_b128 v[54:57], v234 offset:6976
	s_waitcnt lgkmcnt(5)
	v_mfma_f32_16x16x32_bf16 v[38:41], v[58:61], v[74:77], 0
	s_waitcnt lgkmcnt(4)
	v_mfma_f32_16x16x32_bf16 v[38:41], v[62:65], v[78:81], v[38:41]
	ds_read_b128 v[58:61], v234 offset:9216
	ds_read_b128 v[62:65], v234 offset:9280
	s_waitcnt lgkmcnt(5)
	v_mfma_f32_16x16x32_bf16 v[42:45], v[138:141], v[74:77], 0
	s_waitcnt lgkmcnt(4)
	v_mfma_f32_16x16x32_bf16 v[42:45], v[142:145], v[78:81], v[42:45]
	s_waitcnt lgkmcnt(3)
	v_mfma_f32_16x16x32_bf16 v[46:49], v[50:53], v[74:77], 0
	s_waitcnt lgkmcnt(2)
	v_mfma_f32_16x16x32_bf16 v[46:49], v[54:57], v[78:81], v[46:49]
	ds_read_b128 v[50:53], v234 offset:11520
	ds_read_b128 v[54:57], v234 offset:11584
	v_fma_f32 v34, v34, s48, v146
	v_fma_f32 v35, v35, s48, v146
	v_fma_f32 v36, v36, s48, v146
	v_fma_f32 v37, v37, s48, v146
	v_fma_f32 v38, v38, s48, v146
	v_fma_f32 v39, v39, s48, v146
	v_fma_f32 v40, v40, s48, v146
	v_fma_f32 v41, v41, s48, v146
	v_fma_f32 v42, v42, s48, v146
	v_fma_f32 v43, v43, s48, v146
	v_fma_f32 v44, v44, s48, v146
	v_fma_f32 v45, v45, s48, v146
	v_fma_f32 v46, v46, s48, v146
	v_fma_f32 v47, v47, s48, v146
	v_fma_f32 v48, v48, s48, v146
	v_fma_f32 v49, v49, s48, v146
	s_cmp_lg_u32 s76, s72
	s_cbranch_scc1 .Lsb16_nm1_0b
	s_lshl_b32 s83, s76, 6
	v_subrev_u32_e32 v146, s83, v239
	v_add_u32_e32 v146, 2, v146
	v_cmp_le_i32_e64 s[28:29], 0, v146
	s_nop 1
	v_cndmask_b32_e64 v34, v213, v34, s[28:29]
	v_cmp_le_i32_e64 s[28:29], 1, v146
	s_nop 1
	v_cndmask_b32_e64 v35, v213, v35, s[28:29]
	v_cmp_le_i32_e64 s[28:29], 2, v146
	s_nop 1
	v_cndmask_b32_e64 v36, v213, v36, s[28:29]
	v_cmp_le_i32_e64 s[28:29], 3, v146
	s_nop 1
	v_cndmask_b32_e64 v37, v213, v37, s[28:29]
	v_cmp_le_i32_e64 s[28:29], 16, v146
	s_nop 1
	v_cndmask_b32_e64 v38, v213, v38, s[28:29]
	v_cmp_le_i32_e64 s[28:29], 17, v146
	s_nop 1
	v_cndmask_b32_e64 v39, v213, v39, s[28:29]
	v_cmp_le_i32_e64 s[28:29], 18, v146
	s_nop 1
	v_cndmask_b32_e64 v40, v213, v40, s[28:29]
	v_cmp_le_i32_e64 s[28:29], 19, v146
	s_nop 1
	v_cndmask_b32_e64 v41, v213, v41, s[28:29]
	v_cmp_le_i32_e64 s[28:29], 32, v146
	s_nop 1
	v_cndmask_b32_e64 v42, v213, v42, s[28:29]
	v_cmp_le_i32_e64 s[28:29], 33, v146
	s_nop 1
	v_cndmask_b32_e64 v43, v213, v43, s[28:29]
	v_cmp_le_i32_e64 s[28:29], 34, v146
	s_nop 1
	v_cndmask_b32_e64 v44, v213, v44, s[28:29]
	v_cmp_le_i32_e64 s[28:29], 35, v146
	s_nop 1
	v_cndmask_b32_e64 v45, v213, v45, s[28:29]
	v_cmp_le_i32_e64 s[28:29], 48, v146
	s_nop 1
	v_cndmask_b32_e64 v46, v213, v46, s[28:29]
	v_cmp_le_i32_e64 s[28:29], 49, v146
	s_nop 1
	v_cndmask_b32_e64 v47, v213, v47, s[28:29]
	v_cmp_le_i32_e64 s[28:29], 50, v146
	s_nop 1
	v_cndmask_b32_e64 v48, v213, v48, s[28:29]
	v_cmp_le_i32_e64 s[28:29], 51, v146
	s_nop 1
	v_cndmask_b32_e64 v49, v213, v49, s[28:29]
.Lsb16_nm1_0b:
	v_exp_f32_e32 v34, v34
	v_exp_f32_e32 v35, v35
	v_exp_f32_e32 v36, v36
	v_exp_f32_e32 v37, v37
	v_exp_f32_e32 v38, v38
	v_exp_f32_e32 v39, v39
	v_exp_f32_e32 v40, v40
	v_exp_f32_e32 v41, v41
	v_exp_f32_e32 v42, v42
	v_exp_f32_e32 v43, v43
	v_exp_f32_e32 v44, v44
	v_exp_f32_e32 v45, v45
	v_exp_f32_e32 v46, v46
	v_exp_f32_e32 v47, v47
	v_exp_f32_e32 v48, v48
	v_exp_f32_e32 v49, v49
	v_add_f32_e32 v138, v34, v35
	v_add_f32_e32 v139, v36, v37
	v_add_f32_e32 v140, v38, v39
	v_add_f32_e32 v141, v40, v41
	v_add_f32_e32 v138, v138, v42
	v_add_f32_e32 v139, v139, v43
	v_add_f32_e32 v140, v140, v44
	v_add_f32_e32 v141, v141, v45
	v_add_f32_e32 v138, v138, v46
	v_add_f32_e32 v139, v139, v47
	v_add_f32_e32 v140, v140, v48
	v_add_f32_e32 v141, v141, v49
	v_add_f32_e32 v138, v138, v139
	v_add_f32_e32 v140, v140, v141
	v_add_f32_e32 v138, v138, v140
	v_add_f32_e32 v235, v235, v138
	v_cvt_pk_bf16_f32 v138, v34, v35
	v_cvt_pk_bf16_f32 v139, v36, v37
	v_cvt_pk_bf16_f32 v140, v38, v39
	v_cvt_pk_bf16_f32 v141, v40, v41
	v_cvt_pk_bf16_f32 v142, v42, v43
	v_cvt_pk_bf16_f32 v143, v44, v45
	v_cvt_pk_bf16_f32 v144, v46, v47
	v_cvt_pk_bf16_f32 v145, v48, v49
	ds_read_b128 v[34:37], v234 offset:13824
	ds_read_b128 v[38:41], v234 offset:13888
	ds_read_b128 v[42:45], v234 offset:16128
	ds_read_b128 v[46:49], v234 offset:16192
	s_waitcnt lgkmcnt(7)
	v_mfma_f32_16x16x32_bf16 v[18:21], v[58:61], v[138:141], v[18:21]
	s_waitcnt lgkmcnt(6)
	v_mfma_f32_16x16x32_bf16 v[18:21], v[62:65], v[142:145], v[18:21]
	s_waitcnt lgkmcnt(5)
	v_mfma_f32_16x16x32_bf16 v[22:25], v[50:53], v[138:141], v[22:25]
	s_waitcnt lgkmcnt(4)
	v_mfma_f32_16x16x32_bf16 v[22:25], v[54:57], v[142:145], v[22:25]
	s_waitcnt lgkmcnt(3)
	v_mfma_f32_16x16x32_bf16 v[26:29], v[34:37], v[138:141], v[26:29]
	s_waitcnt lgkmcnt(2)
	v_mfma_f32_16x16x32_bf16 v[26:29], v[38:41], v[142:145], v[26:29]
	s_waitcnt lgkmcnt(1)
	v_mfma_f32_16x16x32_bf16 v[30:33], v[42:45], v[138:141], v[30:33]
	s_waitcnt lgkmcnt(0)
	v_mfma_f32_16x16x32_bf16 v[30:33], v[46:49], v[142:145], v[30:33]
	s_branch .Lsb16_end_0
.Lsb16_g1only_0:
	v_subrev_u32_e32 v146, s94, v236
	v_add_u32_e32 v146, 2, v146
	v_lshrrev_b32_e64 v146, v146, s77
	v_and_b32_e32 v146, 1, v146
	v_cmp_ne_u32_e32 vcc, 0, v146
	s_nop 1
	v_cndmask_b32_e32 v146, v213, v100, vcc
	s_waitcnt lgkmcnt(9)
	v_mfma_f32_16x16x32_bf16 v[34:37], v[50:53], v[74:77], 0
	s_waitcnt lgkmcnt(8)
	v_mfma_f32_16x16x32_bf16 v[34:37], v[54:57], v[78:81], v[34:37]
	ds_read_b128 v[50:53], v234 offset:6912
	ds_read_b128 v[54:57], v234 offset:6976
	s_waitcnt lgkmcnt(9)
	v_mfma_f32_16x16x32_bf16 v[38:41], v[58:61], v[74:77], 0
	s_waitcnt lgkmcnt(8)
	v_mfma_f32_16x16x32_bf16 v[38:41], v[62:65], v[78:81], v[38:41]
	ds_read_b128 v[58:61], v234 offset:9216
	ds_read_b128 v[62:65], v234 offset:9280
	s_waitcnt lgkmcnt(9)
	v_mfma_f32_16x16x32_bf16 v[42:45], v[138:141], v[74:77], 0
	s_waitcnt lgkmcnt(8)
	v_mfma_f32_16x16x32_bf16 v[42:45], v[142:145], v[78:81], v[42:45]
	s_waitcnt lgkmcnt(3)
	v_mfma_f32_16x16x32_bf16 v[46:49], v[50:53], v[74:77], 0
	s_waitcnt lgkmcnt(2)
	v_mfma_f32_16x16x32_bf16 v[46:49], v[54:57], v[78:81], v[46:49]
	ds_read_b128 v[50:53], v234 offset:11520
	ds_read_b128 v[54:57], v234 offset:11584
	v_fma_f32 v34, v34, s48, v146
	v_fma_f32 v35, v35, s48, v146
	v_fma_f32 v36, v36, s48, v146
	v_fma_f32 v37, v37, s48, v146
	v_fma_f32 v38, v38, s48, v146
	v_fma_f32 v39, v39, s48, v146
	v_fma_f32 v40, v40, s48, v146
	v_fma_f32 v41, v41, s48, v146
	v_fma_f32 v42, v42, s48, v146
	v_fma_f32 v43, v43, s48, v146
	v_fma_f32 v44, v44, s48, v146
	v_fma_f32 v45, v45, s48, v146
	v_fma_f32 v46, v46, s48, v146
	v_fma_f32 v47, v47, s48, v146
	v_fma_f32 v48, v48, s48, v146
	v_fma_f32 v49, v49, s48, v146
	s_cmp_lg_u32 s76, s72
	s_cbranch_scc1 .Lsb16_nm1_0c
	s_lshl_b32 s83, s76, 6
	v_subrev_u32_e32 v146, s83, v239
	v_add_u32_e32 v146, 2, v146
	v_cmp_le_i32_e64 s[28:29], 0, v146
	s_nop 1
	v_cndmask_b32_e64 v34, v213, v34, s[28:29]
	v_cmp_le_i32_e64 s[28:29], 1, v146
	s_nop 1
	v_cndmask_b32_e64 v35, v213, v35, s[28:29]
	v_cmp_le_i32_e64 s[28:29], 2, v146
	s_nop 1
	v_cndmask_b32_e64 v36, v213, v36, s[28:29]
	v_cmp_le_i32_e64 s[28:29], 3, v146
	s_nop 1
	v_cndmask_b32_e64 v37, v213, v37, s[28:29]
	v_cmp_le_i32_e64 s[28:29], 16, v146
	s_nop 1
	v_cndmask_b32_e64 v38, v213, v38, s[28:29]
	v_cmp_le_i32_e64 s[28:29], 17, v146
	s_nop 1
	v_cndmask_b32_e64 v39, v213, v39, s[28:29]
	v_cmp_le_i32_e64 s[28:29], 18, v146
	s_nop 1
	v_cndmask_b32_e64 v40, v213, v40, s[28:29]
	v_cmp_le_i32_e64 s[28:29], 19, v146
	s_nop 1
	v_cndmask_b32_e64 v41, v213, v41, s[28:29]
	v_cmp_le_i32_e64 s[28:29], 32, v146
	s_nop 1
	v_cndmask_b32_e64 v42, v213, v42, s[28:29]
	v_cmp_le_i32_e64 s[28:29], 33, v146
	s_nop 1
	v_cndmask_b32_e64 v43, v213, v43, s[28:29]
	v_cmp_le_i32_e64 s[28:29], 34, v146
	s_nop 1
	v_cndmask_b32_e64 v44, v213, v44, s[28:29]
	v_cmp_le_i32_e64 s[28:29], 35, v146
	s_nop 1
	v_cndmask_b32_e64 v45, v213, v45, s[28:29]
	v_cmp_le_i32_e64 s[28:29], 48, v146
	s_nop 1
	v_cndmask_b32_e64 v46, v213, v46, s[28:29]
	v_cmp_le_i32_e64 s[28:29], 49, v146
	s_nop 1
	v_cndmask_b32_e64 v47, v213, v47, s[28:29]
	v_cmp_le_i32_e64 s[28:29], 50, v146
	s_nop 1
	v_cndmask_b32_e64 v48, v213, v48, s[28:29]
	v_cmp_le_i32_e64 s[28:29], 51, v146
	s_nop 1
	v_cndmask_b32_e64 v49, v213, v49, s[28:29]

.Lsb16_nost_i_0:
.Lsb16_done_i_0:
.Lsb16_end_0:
	s_add_i32 s25, s25, 1
	s_cmp_eq_u32 s25, s101
	s_waitcnt lgkmcnt(0)
	s_barrier
	s_cbranch_scc1 .LBB0_2180
.Lsb16_step_1:
	s_and_b32 s38, s25, 63
	v_readlane_b32 s32, v136, s38
	v_readlane_b32 s38, v137, s38
	s_bitcmp1_b32 s25, 6
	s_cselect_b32 s77, s38, s32
	s_and_b32 s56, s77, s86
	s_and_b32 s57, s77, s87
	s_or_b32 s28, s56, s57
	s_cmp_eq_u32 s28, 0
	s_cbranch_scc1 .Lsb16_idle_1
	s_and_b32 s38, s25, 63
	v_readlane_b32 s32, v133, s38
	v_readlane_b32 s38, v148, s38
	s_bitcmp1_b32 s25, 6
	s_cselect_b32 s76, s38, s32
	ds_read_b128 v[50:53], v234 offset:18432
	ds_read_b128 v[54:57], v234 offset:18496
	ds_read_b128 v[58:61], v234 offset:20736
	ds_read_b128 v[62:65], v234 offset:20800
	ds_read_b128 v[138:141], v234 offset:23040
	ds_read_b128 v[142:145], v234 offset:23104
	s_add_i32 s58, s25, 1
	s_cmp_ge_u32 s58, s101
	s_cbranch_scc1 .Lsb16_nost_a_1
	s_add_i32 s58, s25, 2
	s_cmp_ge_u32 s58, s101
	s_cbranch_scc1 .Lsb16_w0_a_1
	s_waitcnt vmcnt(4)
	s_branch .Lsb16_wr_a_1

.Lsb16_wr_a_1:
	ds_write_b128 v153, v[82:85]
	ds_write_b128 v153, v[86:89] offset:9216
	ds_write_b128 v155, v[90:93]
	ds_write_b128 v155, v[94:97] offset:9216
	s_add_i32 s58, s25, 3
	s_cmp_ge_u32 s58, s101
	s_cbranch_scc1 .Lsb16_done_a_1
	s_and_b32 s38, s58, 63
	v_readlane_b32 s32, v133, s38
	v_readlane_b32 s38, v148, s38
	s_bitcmp1_b32 s58, 6
	s_cselect_b32 s32, s38, s32
	s_lshl_b32 s32, s32, 13
	s_add_u32 s28, s20, s32
	s_addc_u32 s29, s21, 0
	s_add_u32 s82, s22, s32
	s_addc_u32 s83, s23, 0
	global_load_dwordx4 v[82:85], v134, s[28:29]
	global_load_dwordx4 v[86:89], v134, s[82:83]
	global_load_dwordx4 v[90:93], v135, s[28:29]
	global_load_dwordx4 v[94:97], v135, s[82:83]
	s_branch .Lsb16_done_a_1

.Lsb16_done_a_1:
	s_cmp_eq_u32 s56, 0
	s_cbranch_scc1 .Lsb16_g1only_1
	v_subrev_u32_e32 v146, s94, v236
	v_lshrrev_b32_e64 v146, v146, s77
	v_and_b32_e32 v146, 1, v146
	v_cmp_ne_u32_e32 vcc, 0, v146
	s_nop 1
	v_cndmask_b32_e32 v146, v213, v100, vcc
	s_waitcnt lgkmcnt(9)
	v_mfma_f32_16x16x32_bf16 v[34:37], v[50:53], v[66:69], 0
	s_waitcnt lgkmcnt(8)
	v_mfma_f32_16x16x32_bf16 v[34:37], v[54:57], v[70:73], v[34:37]
	ds_read_b128 v[50:53], v234 offset:25344
	ds_read_b128 v[54:57], v234 offset:25408
	s_waitcnt lgkmcnt(9)
	v_mfma_f32_16x16x32_bf16 v[38:41], v[58:61], v[66:69], 0
	s_waitcnt lgkmcnt(8)
	v_mfma_f32_16x16x32_bf16 v[38:41], v[62:65], v[70:73], v[38:41]
	ds_read_b128 v[58:61], v234 offset:27648
	ds_read_b128 v[62:65], v234 offset:27712
	s_waitcnt lgkmcnt(9)
	v_mfma_f32_16x16x32_bf16 v[42:45], v[138:141], v[66:69], 0
	s_waitcnt lgkmcnt(8)
	v_mfma_f32_16x16x32_bf16 v[42:45], v[142:145], v[70:73], v[42:45]
	s_waitcnt lgkmcnt(3)
	v_mfma_f32_16x16x32_bf16 v[46:49], v[50:53], v[66:69], 0
	s_waitcnt lgkmcnt(2)
	v_mfma_f32_16x16x32_bf16 v[46:49], v[54:57], v[70:73], v[46:49]
	ds_read_b128 v[50:53], v234 offset:29952
	ds_read_b128 v[54:57], v234 offset:30016
	v_fma_f32 v34, v34, s48, v146
	v_fma_f32 v35, v35, s48, v146
	v_fma_f32 v36, v36, s48, v146
	v_fma_f32 v37, v37, s48, v146
	v_fma_f32 v38, v38, s48, v146
	v_fma_f32 v39, v39, s48, v146
	v_fma_f32 v40, v40, s48, v146
	v_fma_f32 v41, v41, s48, v146
	v_fma_f32 v42, v42, s48, v146
	v_fma_f32 v43, v43, s48, v146
	v_fma_f32 v44, v44, s48, v146
	v_fma_f32 v45, v45, s48, v146
	v_fma_f32 v46, v46, s48, v146
	v_fma_f32 v47, v47, s48, v146
	v_fma_f32 v48, v48, s48, v146
	v_fma_f32 v49, v49, s48, v146
	s_cmp_lg_u32 s76, s72
	s_cbranch_scc1 .Lsb16_nm0_1a
	s_lshl_b32 s83, s76, 6
	v_subrev_u32_e32 v146, s83, v239
	v_cmp_le_i32_e64 s[28:29], 0, v146
	s_nop 1
	v_cndmask_b32_e64 v34, v213, v34, s[28:29]
	v_cmp_le_i32_e64 s[28:29], 1, v146
	s_nop 1
	v_cndmask_b32_e64 v35, v213, v35, s[28:29]
	v_cmp_le_i32_e64 s[28:29], 2, v146
	s_nop 1
	v_cndmask_b32_e64 v36, v213, v36, s[28:29]
	v_cmp_le_i32_e64 s[28:29], 3, v146
	s_nop 1
	v_cndmask_b32_e64 v37, v213, v37, s[28:29]
	v_cmp_le_i32_e64 s[28:29], 16, v146
	s_nop 1
	v_cndmask_b32_e64 v38, v213, v38, s[28:29]
	v_cmp_le_i32_e64 s[28:29], 17, v146
	s_nop 1
	v_cndmask_b32_e64 v39, v213, v39, s[28:29]
	v_cmp_le_i32_e64 s[28:29], 18, v146
	s_nop 1
	v_cndmask_b32_e64 v40, v213, v40, s[28:29]
	v_cmp_le_i32_e64 s[28:29], 19, v146
	s_nop 1
	v_cndmask_b32_e64 v41, v213, v41, s[28:29]
	v_cmp_le_i32_e64 s[28:29], 32, v146
	s_nop 1
	v_cndmask_b32_e64 v42, v213, v42, s[28:29]
	v_cmp_le_i32_e64 s[28:29], 33, v146
	s_nop 1
	v_cndmask_b32_e64 v43, v213, v43, s[28:29]
	v_cmp_le_i32_e64 s[28:29], 34, v146
	s_nop 1
	v_cndmask_b32_e64 v44, v213, v44, s[28:29]
	v_cmp_le_i32_e64 s[28:29], 35, v146
	s_nop 1
	v_cndmask_b32_e64 v45, v213, v45, s[28:29]
	v_cmp_le_i32_e64 s[28:29], 48, v146
	s_nop 1
	v_cndmask_b32_e64 v46, v213, v46, s[28:29]
	v_cmp_le_i32_e64 s[28:29], 49, v146
	s_nop 1
	v_cndmask_b32_e64 v47, v213, v47, s[28:29]
	v_cmp_le_i32_e64 s[28:29], 50, v146
	s_nop 1
	v_cndmask_b32_e64 v48, v213, v48, s[28:29]
	v_cmp_le_i32_e64 s[28:29], 51, v146
	s_nop 1
	v_cndmask_b32_e64 v49, v213, v49, s[28:29]
.Lsb16_nm0_1a:
	v_exp_f32_e32 v34, v34
	v_exp_f32_e32 v35, v35
	v_exp_f32_e32 v36, v36
	v_exp_f32_e32 v37, v37
	v_exp_f32_e32 v38, v38
	v_exp_f32_e32 v39, v39
	v_exp_f32_e32 v40, v40
	v_exp_f32_e32 v41, v41
	v_exp_f32_e32 v42, v42
	v_exp_f32_e32 v43, v43
	v_exp_f32_e32 v44, v44
	v_exp_f32_e32 v45, v45
	v_exp_f32_e32 v46, v46
	v_exp_f32_e32 v47, v47
	v_exp_f32_e32 v48, v48
	v_exp_f32_e32 v49, v49
	v_add_f32_e32 v138, v34, v35
	v_add_f32_e32 v139, v36, v37
	v_add_f32_e32 v140, v38, v39
	v_add_f32_e32 v141, v40, v41
	v_add_f32_e32 v138, v138, v42
	v_add_f32_e32 v139, v139, v43
	v_add_f32_e32 v140, v140, v44
	v_add_f32_e32 v141, v141, v45
	v_add_f32_e32 v138, v138, v46
	v_add_f32_e32 v139, v139, v47
	v_add_f32_e32 v140, v140, v48
	v_add_f32_e32 v141, v141, v49
	v_add_f32_e32 v138, v138, v139
	v_add_f32_e32 v140, v140, v141
	v_add_f32_e32 v138, v138, v140
	v_add_f32_e32 v129, v129, v138
	v_cvt_pk_bf16_f32 v138, v34, v35
	v_cvt_pk_bf16_f32 v139, v36, v37
	v_cvt_pk_bf16_f32 v140, v38, v39
	v_cvt_pk_bf16_f32 v141, v40, v41
	v_cvt_pk_bf16_f32 v142, v42, v43
	v_cvt_pk_bf16_f32 v143, v44, v45
	v_cvt_pk_bf16_f32 v144, v46, v47
	v_cvt_pk_bf16_f32 v145, v48, v49
	ds_read_b128 v[34:37], v234 offset:32256
	ds_read_b128 v[38:41], v234 offset:32320
	ds_read_b128 v[42:45], v234 offset:34560
	ds_read_b128 v[46:49], v234 offset:34624
	s_waitcnt lgkmcnt(7)
	v_mfma_f32_16x16x32_bf16 v[2:5], v[58:61], v[138:141], v[2:5]
	s_waitcnt lgkmcnt(6)
	v_mfma_f32_16x16x32_bf16 v[2:5], v[62:65], v[142:145], v[2:5]
	s_waitcnt lgkmcnt(5)
	v_mfma_f32_16x16x32_bf16 v[6:9], v[50:53], v[138:141], v[6:9]
	s_waitcnt lgkmcnt(4)
	v_mfma_f32_16x16x32_bf16 v[6:9], v[54:57], v[142:145], v[6:9]
	s_waitcnt lgkmcnt(3)
	v_mfma_f32_16x16x32_bf16 v[10:13], v[34:37], v[138:141], v[10:13]
	s_waitcnt lgkmcnt(2)
	v_mfma_f32_16x16x32_bf16 v[10:13], v[38:41], v[142:145], v[10:13]
	s_waitcnt lgkmcnt(1)
	v_mfma_f32_16x16x32_bf16 v[14:17], v[42:45], v[138:141], v[14:17]
	s_waitcnt lgkmcnt(0)
	v_mfma_f32_16x16x32_bf16 v[14:17], v[46:49], v[142:145], v[14:17]
	s_cmp_eq_u32 s57, 0
	s_cbranch_scc1 .Lsb16_end_1
	ds_read_b128 v[50:53], v234 offset:18432
	ds_read_b128 v[54:57], v234 offset:18496
	ds_read_b128 v[58:61], v234 offset:20736
	ds_read_b128 v[62:65], v234 offset:20800
	ds_read_b128 v[138:141], v234 offset:23040
	ds_read_b128 v[142:145], v234 offset:23104
	v_subrev_u32_e32 v146, s94, v236
	v_add_u32_e32 v146, 2, v146
	v_lshrrev_b32_e64 v146, v146, s77
	v_and_b32_e32 v146, 1, v146
	v_cmp_ne_u32_e32 vcc, 0, v146
	s_nop 1
	v_cndmask_b32_e32 v146, v213, v100, vcc
	s_waitcnt lgkmcnt(5)
	v_mfma_f32_16x16x32_bf16 v[34:37], v[50:53], v[74:77], 0
	s_waitcnt lgkmcnt(4)
	v_mfma_f32_16x16x32_bf16 v[34:37], v[54:57], v[78:81], v[34:37]
	ds_read_b128 v[50:53], v234 offset:25344
	ds_read_b128 v[54:57], v234 offset:25408
	s_waitcnt lgkmcnt(5)
	v_mfma_f32_16x16x32_bf16 v[38:41], v[58:61], v[74:77], 0
	s_waitcnt lgkmcnt(4)
	v_mfma_f32_16x16x32_bf16 v[38:41], v[62:65], v[78:81], v[38:41]
	ds_read_b128 v[58:61], v234 offset:27648
	ds_read_b128 v[62:65], v234 offset:27712
	s_waitcnt lgkmcnt(5)
	v_mfma_f32_16x16x32_bf16 v[42:45], v[138:141], v[74:77], 0
	s_waitcnt lgkmcnt(4)
	v_mfma_f32_16x16x32_bf16 v[42:45], v[142:145], v[78:81], v[42:45]
	s_waitcnt lgkmcnt(3)
	v_mfma_f32_16x16x32_bf16 v[46:49], v[50:53], v[74:77], 0
	s_waitcnt lgkmcnt(2)
	v_mfma_f32_16x16x32_bf16 v[46:49], v[54:57], v[78:81], v[46:49]
	ds_read_b128 v[50:53], v234 offset:29952
	ds_read_b128 v[54:57], v234 offset:30016
	v_fma_f32 v34, v34, s48, v146
	v_fma_f32 v35, v35, s48, v146
	v_fma_f32 v36, v36, s48, v146
	v_fma_f32 v37, v37, s48, v146
	v_fma_f32 v38, v38, s48, v146
	v_fma_f32 v39, v39, s48, v146
	v_fma_f32 v40, v40, s48, v146
	v_fma_f32 v41, v41, s48, v146
	v_fma_f32 v42, v42, s48, v146
	v_fma_f32 v43, v43, s48, v146
	v_fma_f32 v44, v44, s48, v146
	v_fma_f32 v45, v45, s48, v146
	v_fma_f32 v46, v46, s48, v146
	v_fma_f32 v47, v47, s48, v146
	v_fma_f32 v48, v48, s48, v146
	v_fma_f32 v49, v49, s48, v146
	s_cmp_lg_u32 s76, s72
	s_cbranch_scc1 .Lsb16_nm1_1b
	s_lshl_b32 s83, s76, 6
	v_subrev_u32_e32 v146, s83, v239
	v_add_u32_e32 v146, 2, v146
	v_cmp_le_i32_e64 s[28:29], 0, v146
	s_nop 1
	v_cndmask_b32_e64 v34, v213, v34, s[28:29]
	v_cmp_le_i32_e64 s[28:29], 1, v146
	s_nop 1
	v_cndmask_b32_e64 v35, v213, v35, s[28:29]
	v_cmp_le_i32_e64 s[28:29], 2, v146
	s_nop 1
	v_cndmask_b32_e64 v36, v213, v36, s[28:29]
	v_cmp_le_i32_e64 s[28:29], 3, v146
	s_nop 1
	v_cndmask_b32_e64 v37, v213, v37, s[28:29]
	v_cmp_le_i32_e64 s[28:29], 16, v146
	s_nop 1
	v_cndmask_b32_e64 v38, v213, v38, s[28:29]
	v_cmp_le_i32_e64 s[28:29], 17, v146
	s_nop 1
	v_cndmask_b32_e64 v39, v213, v39, s[28:29]
	v_cmp_le_i32_e64 s[28:29], 18, v146
	s_nop 1
	v_cndmask_b32_e64 v40, v213, v40, s[28:29]
	v_cmp_le_i32_e64 s[28:29], 19, v146
	s_nop 1
	v_cndmask_b32_e64 v41, v213, v41, s[28:29]
	v_cmp_le_i32_e64 s[28:29], 32, v146
	s_nop 1
	v_cndmask_b32_e64 v42, v213, v42, s[28:29]
	v_cmp_le_i32_e64 s[28:29], 33, v146
	s_nop 1
	v_cndmask_b32_e64 v43, v213, v43, s[28:29]
	v_cmp_le_i32_e64 s[28:29], 34, v146
	s_nop 1
	v_cndmask_b32_e64 v44, v213, v44, s[28:29]
	v_cmp_le_i32_e64 s[28:29], 35, v146
	s_nop 1
	v_cndmask_b32_e64 v45, v213, v45, s[28:29]
	v_cmp_le_i32_e64 s[28:29], 48, v146
	s_nop 1
	v_cndmask_b32_e64 v46, v213, v46, s[28:29]
	v_cmp_le_i32_e64 s[28:29], 49, v146
	s_nop 1
	v_cndmask_b32_e64 v47, v213, v47, s[28:29]
	v_cmp_le_i32_e64 s[28:29], 50, v146
	s_nop 1
	v_cndmask_b32_e64 v48, v213, v48, s[28:29]
	v_cmp_le_i32_e64 s[28:29], 51, v146
	s_nop 1
	v_cndmask_b32_e64 v49, v213, v49, s[28:29]
.Lsb16_nm1_1b:
	v_exp_f32_e32 v34, v34
	v_exp_f32_e32 v35, v35
	v_exp_f32_e32 v36, v36
	v_exp_f32_e32 v37, v37
	v_exp_f32_e32 v38, v38
	v_exp_f32_e32 v39, v39
	v_exp_f32_e32 v40, v40
	v_exp_f32_e32 v41, v41
	v_exp_f32_e32 v42, v42
	v_exp_f32_e32 v43, v43
	v_exp_f32_e32 v44, v44
	v_exp_f32_e32 v45, v45
	v_exp_f32_e32 v46, v46
	v_exp_f32_e32 v47, v47
	v_exp_f32_e32 v48, v48
	v_exp_f32_e32 v49, v49
	v_add_f32_e32 v138, v34, v35
	v_add_f32_e32 v139, v36, v37
	v_add_f32_e32 v140, v38, v39
	v_add_f32_e32 v141, v40, v41
	v_add_f32_e32 v138, v138, v42
	v_add_f32_e32 v139, v139, v43
	v_add_f32_e32 v140, v140, v44
	v_add_f32_e32 v141, v141, v45
	v_add_f32_e32 v138, v138, v46
	v_add_f32_e32 v139, v139, v47
	v_add_f32_e32 v140, v140, v48
	v_add_f32_e32 v141, v141, v49
	v_add_f32_e32 v138, v138, v139
	v_add_f32_e32 v140, v140, v141
	v_add_f32_e32 v138, v138, v140
	v_add_f32_e32 v235, v235, v138
	v_cvt_pk_bf16_f32 v138, v34, v35
	v_cvt_pk_bf16_f32 v139, v36, v37
	v_cvt_pk_bf16_f32 v140, v38, v39
	v_cvt_pk_bf16_f32 v141, v40, v41
	v_cvt_pk_bf16_f32 v142, v42, v43
	v_cvt_pk_bf16_f32 v143, v44, v45
	v_cvt_pk_bf16_f32 v144, v46, v47
	v_cvt_pk_bf16_f32 v145, v48, v49
	ds_read_b128 v[34:37], v234 offset:32256
	ds_read_b128 v[38:41], v234 offset:32320
	ds_read_b128 v[42:45], v234 offset:34560
	ds_read_b128 v[46:49], v234 offset:34624
	s_waitcnt lgkmcnt(7)
	v_mfma_f32_16x16x32_bf16 v[18:21], v[58:61], v[138:141], v[18:21]
	s_waitcnt lgkmcnt(6)
	v_mfma_f32_16x16x32_bf16 v[18:21], v[62:65], v[142:145], v[18:21]
	s_waitcnt lgkmcnt(5)
	v_mfma_f32_16x16x32_bf16 v[22:25], v[50:53], v[138:141], v[22:25]
	s_waitcnt lgkmcnt(4)
	v_mfma_f32_16x16x32_bf16 v[22:25], v[54:57], v[142:145], v[22:25]
	s_waitcnt lgkmcnt(3)
	v_mfma_f32_16x16x32_bf16 v[26:29], v[34:37], v[138:141], v[26:29]
	s_waitcnt lgkmcnt(2)
	v_mfma_f32_16x16x32_bf16 v[26:29], v[38:41], v[142:145], v[26:29]
	s_waitcnt lgkmcnt(1)
	v_mfma_f32_16x16x32_bf16 v[30:33], v[42:45], v[138:141], v[30:33]
	s_waitcnt lgkmcnt(0)
	v_mfma_f32_16x16x32_bf16 v[30:33], v[46:49], v[142:145], v[30:33]
	s_branch .Lsb16_end_1
.Lsb16_g1only_1:
	v_subrev_u32_e32 v146, s94, v236
	v_add_u32_e32 v146, 2, v146
	v_lshrrev_b32_e64 v146, v146, s77
	v_and_b32_e32 v146, 1, v146
	v_cmp_ne_u32_e32 vcc, 0, v146
	s_nop 1
	v_cndmask_b32_e32 v146, v213, v100, vcc
	s_waitcnt lgkmcnt(9)
	v_mfma_f32_16x16x32_bf16 v[34:37], v[50:53], v[74:77], 0
	s_waitcnt lgkmcnt(8)
	v_mfma_f32_16x16x32_bf16 v[34:37], v[54:57], v[78:81], v[34:37]
	ds_read_b128 v[50:53], v234 offset:25344
	ds_read_b128 v[54:57], v234 offset:25408
	s_waitcnt lgkmcnt(9)
	v_mfma_f32_16x16x32_bf16 v[38:41], v[58:61], v[74:77], 0
	s_waitcnt lgkmcnt(8)
	v_mfma_f32_16x16x32_bf16 v[38:41], v[62:65], v[78:81], v[38:41]
	ds_read_b128 v[58:61], v234 offset:27648
	ds_read_b128 v[62:65], v234 offset:27712
	s_waitcnt lgkmcnt(9)
	v_mfma_f32_16x16x32_bf16 v[42:45], v[138:141], v[74:77], 0
	s_waitcnt lgkmcnt(8)
	v_mfma_f32_16x16x32_bf16 v[42:45], v[142:145], v[78:81], v[42:45]
	s_waitcnt lgkmcnt(3)
	v_mfma_f32_16x16x32_bf16 v[46:49], v[50:53], v[74:77], 0
	s_waitcnt lgkmcnt(2)
	v_mfma_f32_16x16x32_bf16 v[46:49], v[54:57], v[78:81], v[46:49]
	ds_read_b128 v[50:53], v234 offset:29952
	ds_read_b128 v[54:57], v234 offset:30016
	v_fma_f32 v34, v34, s48, v146
	v_fma_f32 v35, v35, s48, v146
	v_fma_f32 v36, v36, s48, v146
	v_fma_f32 v37, v37, s48, v146
	v_fma_f32 v38, v38, s48, v146
	v_fma_f32 v39, v39, s48, v146
	v_fma_f32 v40, v40, s48, v146
	v_fma_f32 v41, v41, s48, v146
	v_fma_f32 v42, v42, s48, v146
	v_fma_f32 v43, v43, s48, v146
	v_fma_f32 v44, v44, s48, v146
	v_fma_f32 v45, v45, s48, v146
	v_fma_f32 v46, v46, s48, v146
	v_fma_f32 v47, v47, s48, v146
	v_fma_f32 v48, v48, s48, v146
	v_fma_f32 v49, v49, s48, v146
	s_cmp_lg_u32 s76, s72
	s_cbranch_scc1 .Lsb16_nm1_1c
	s_lshl_b32 s83, s76, 6
	v_subrev_u32_e32 v146, s83, v239
	v_add_u32_e32 v146, 2, v146
	v_cmp_le_i32_e64 s[28:29], 0, v146
	s_nop 1
	v_cndmask_b32_e64 v34, v213, v34, s[28:29]
	v_cmp_le_i32_e64 s[28:29], 1, v146
	s_nop 1
	v_cndmask_b32_e64 v35, v213, v35, s[28:29]
	v_cmp_le_i32_e64 s[28:29], 2, v146
	s_nop 1
	v_cndmask_b32_e64 v36, v213, v36, s[28:29]
	v_cmp_le_i32_e64 s[28:29], 3, v146
	s_nop 1
	v_cndmask_b32_e64 v37, v213, v37, s[28:29]
	v_cmp_le_i32_e64 s[28:29], 16, v146
	s_nop 1
	v_cndmask_b32_e64 v38, v213, v38, s[28:29]
	v_cmp_le_i32_e64 s[28:29], 17, v146
	s_nop 1
	v_cndmask_b32_e64 v39, v213, v39, s[28:29]
	v_cmp_le_i32_e64 s[28:29], 18, v146
	s_nop 1
	v_cndmask_b32_e64 v40, v213, v40, s[28:29]
	v_cmp_le_i32_e64 s[28:29], 19, v146
	s_nop 1
	v_cndmask_b32_e64 v41, v213, v41, s[28:29]
	v_cmp_le_i32_e64 s[28:29], 32, v146
	s_nop 1
	v_cndmask_b32_e64 v42, v213, v42, s[28:29]
	v_cmp_le_i32_e64 s[28:29], 33, v146
	s_nop 1
	v_cndmask_b32_e64 v43, v213, v43, s[28:29]
	v_cmp_le_i32_e64 s[28:29], 34, v146
	s_nop 1
	v_cndmask_b32_e64 v44, v213, v44, s[28:29]
	v_cmp_le_i32_e64 s[28:29], 35, v146
	s_nop 1
	v_cndmask_b32_e64 v45, v213, v45, s[28:29]
	v_cmp_le_i32_e64 s[28:29], 48, v146
	s_nop 1
	v_cndmask_b32_e64 v46, v213, v46, s[28:29]
	v_cmp_le_i32_e64 s[28:29], 49, v146
	s_nop 1
	v_cndmask_b32_e64 v47, v213, v47, s[28:29]
	v_cmp_le_i32_e64 s[28:29], 50, v146
	s_nop 1
	v_cndmask_b32_e64 v48, v213, v48, s[28:29]
	v_cmp_le_i32_e64 s[28:29], 51, v146
	s_nop 1
	v_cndmask_b32_e64 v49, v213, v49, s[28:29]

.Lsb16_nost_i_1:
.Lsb16_done_i_1:
.Lsb16_end_1:
	s_add_i32 s25, s25, 1
	s_cmp_eq_u32 s25, s101
	s_waitcnt lgkmcnt(0)
	s_barrier
	s_cbranch_scc1 .LBB0_2180
	s_branch .Lsb16_step_0
